# seam-0 barrier: member workgroups poll the top release word directly (one hop less on the release path)
# baseline (speedup 1.0000x reference)
.Lgs_grp:
	s_sleep 1
	global_load_dword v3, v1, s[8:9] offset:2208 sc1
	s_waitcnt vmcnt(0)
	v_readfirstlane_b32 s12, v3
	s_add_u32 s13, s13, 1
	s_cmp_lg_u32 s12, 0
	s_cbranch_scc1 .Lgs_grp_ok
	s_cmp_lt_u32 s13, 0x4000
	s_cbranch_scc1 .Lgs_grp
.Lgs_grp_ok:
.Lgs_done:
	s_waitcnt vmcnt(0)
